# strategy 7 packed ops: NSA sliding-window PV block subtracts the running max pairwise with v_pk_add_f32 and drops the add-zero at the head of the probability sum
# speedup vs baseline: 1.0082x; 1.0082x over previous
; #define EXP2F(x) __builtin_amdgcn_exp2f(x)
; #define SB0 __builtin_amdgcn_sched_barrier(0)
; __device__ __forceinline__ void pv64(const bf16x8 (&vq)[8], const f32x4 (&pr)[4], f32x4 (&o)[4]) {
; #pragma unroll
;   for (int hf = 0; hf < 2; ++hf) {
;     uint4 pw;
;     pw.x = pack2bf(pr[2 * hf][0], pr[2 * hf][1]); pw.y = pack2bf(pr[2 * hf][2], pr[2 * hf][3]);
;     pw.z = pack2bf(pr[2 * hf + 1][0], pr[2 * hf + 1][1]); pw.w = pack2bf(pr[2 * hf + 1][2], pr[2 * hf + 1][3]);
;     const bf16x8 pb = __builtin_bit_cast(bf16x8, pw);
; #pragma unroll
;     for (int dt = 0; dt < 4; ++dt) o[dt] = mfma16(vq[dt * 2 + hf], pb, o[dt]);
;   }
; }
; __device__ __forceinline__ void softmax_update(f32x4 (&st)[4], float& m, float& lsum, f32x4 (&o)[4]) {
;   float mx = -1e30f;
; #pragma unroll
;   for (int kt = 0; kt < 4; ++kt)
; #pragma unroll
;     for (int r = 0; r < 4; ++r) mx = fmaxf(mx, st[kt][r]);
;   mx = fmaxf(mx, __shfl_xor(mx, 16));
;   mx = fmaxf(mx, __shfl_xor(mx, 32));
;   const float mnew = fmaxf(m, mx);
;   const float alpha = EXP2F(m - mnew);
;   float ps = 0.f;
; #pragma unroll
;   for (int kt = 0; kt < 4; ++kt)
; #pragma unroll
;     for (int r = 0; r < 4; ++r) {
;       const float pv = EXP2F(st[kt][r] - mnew);
;       st[kt][r] = pv;
;       ps += pv;
;     }
;   lsum = lsum * alpha + ps;
;   m = mnew;
;   if (__builtin_amdgcn_ballot_w64(alpha != 1.0f)) {
; #pragma unroll
;     for (int dt = 0; dt < 4; ++dt) o[dt] *= alpha;
;   }
; }
; __device__ __forceinline__ void phase_nsa_attn(const Params& p, char* smem, volatile LAS unsigned* vb_) {
;     ...
;         softmax_update(st, m, lsum, o);
;         pv64(vA, st, o);
;         SB0;
;         v_load64(vA, Vw + (size_t)kx * 64, lane);
;         SB0;
.LBB0_102:
	v_sub_f32_e32 v99, v99, v98
	v_exp_f32_e32 v115, v99
	v_pk_add_f32 v[100:101], v[100:101], v[98:99] op_sel_hi:[1,0] neg_lo:[0,1] neg_hi:[0,1]
	v_exp_f32_e32 v100, v100
	v_exp_f32_e32 v101, v101
	v_pk_add_f32 v[102:103], v[102:103], v[98:99] op_sel_hi:[1,0] neg_lo:[0,1] neg_hi:[0,1]
	v_exp_f32_e32 v102, v102
	v_exp_f32_e32 v103, v103
	v_pk_add_f32 v[104:105], v[104:105], v[98:99] op_sel_hi:[1,0] neg_lo:[0,1] neg_hi:[0,1]
	v_add_f32_e32 v99, v100, v115
	v_exp_f32_e32 v104, v104
	v_add_f32_e32 v99, v101, v99
	v_exp_f32_e32 v105, v105
	v_pk_add_f32 v[106:107], v[106:107], v[98:99] op_sel_hi:[1,0] neg_lo:[0,1] neg_hi:[0,1]
	v_add_f32_e32 v99, v102, v99
	v_exp_f32_e32 v106, v106
	v_add_f32_e32 v99, v103, v99
	v_exp_f32_e32 v107, v107
	v_pk_add_f32 v[108:109], v[108:109], v[98:99] op_sel_hi:[1,0] neg_lo:[0,1] neg_hi:[0,1]
	v_add_f32_e32 v99, v104, v99
	v_exp_f32_e32 v108, v108
	v_add_f32_e32 v99, v105, v99
	v_exp_f32_e32 v109, v109
	v_pk_add_f32 v[110:111], v[110:111], v[98:99] op_sel_hi:[1,0] neg_lo:[0,1] neg_hi:[0,1]
	v_add_f32_e32 v99, v106, v99
	v_exp_f32_e32 v110, v110
	v_pk_add_f32 v[112:113], v[112:113], v[98:99] op_sel_hi:[1,0] neg_lo:[0,1] neg_hi:[0,1]
	v_sub_f32_e32 v114, v114, v98
	v_add_f32_e32 v99, v107, v99
	v_exp_f32_e32 v111, v111
	v_exp_f32_e32 v112, v112
	v_exp_f32_e32 v113, v113
	v_exp_f32_e32 v114, v114
	v_cvt_pk_bf16_f32 v100, v115, v100
	v_cvt_pk_bf16_f32 v101, v101, v102
	v_cvt_pk_bf16_f32 v102, v103, v104
	v_cvt_pk_bf16_f32 v103, v105, v106
	v_add_f32_e32 v99, v108, v99
	v_add_f32_e32 v99, v109, v99
	s_waitcnt vmcnt(15)
	v_mfma_f32_16x16x32_bf16 v[24:27], v[64:67], v[100:103], v[24:27]
	v_add_f32_e32 v99, v110, v99
	v_add_f32_e32 v99, v111, v99
	v_add_f32_e32 v99, v112, v99
	s_waitcnt vmcnt(13)
	v_mfma_f32_16x16x32_bf16 v[20:23], v[56:59], v[100:103], v[20:23]
	v_add_f32_e32 v99, v113, v99
	v_add_f32_e32 v99, v114, v99
	v_fmac_f32_e32 v99, v97, v92
	s_waitcnt vmcnt(11)
	v_mfma_f32_16x16x32_bf16 v[16:19], v[60:63], v[100:103], v[16:19]
	v_lshlrev_b64 v[2:3], 6, v[2:3]
	s_waitcnt vmcnt(9)
	v_mfma_f32_16x16x32_bf16 v[12:15], v[48:51], v[100:103], v[12:15]
	v_cvt_pk_bf16_f32 v48, v107, v108
	v_cvt_pk_bf16_f32 v49, v109, v110
	v_cvt_pk_bf16_f32 v50, v111, v112
	v_cvt_pk_bf16_f32 v51, v113, v114
	s_nop 1
	v_mfma_f32_16x16x32_bf16 v[24:27], v[40:43], v[48:51], v[24:27]
	v_mfma_f32_16x16x32_bf16 v[20:23], v[32:35], v[48:51], v[20:23]
	v_mfma_f32_16x16x32_bf16 v[16:19], v[36:39], v[48:51], v[16:19]
	s_waitcnt vmcnt(8)
	v_mfma_f32_16x16x32_bf16 v[12:15], v[28:31], v[48:51], v[12:15]
	v_lshl_add_u64 v[2:3], v[2:3], 1, v[144:145]
	global_load_dwordx4 v[64:67], v[2:3], off
	global_load_dwordx4 v[40:43], v[2:3], off offset:1024
	global_load_dwordx4 v[56:59], v[2:3], off offset:2048
	global_load_dwordx4 v[32:35], v[2:3], off offset:3072
	v_add_co_u32_e32 v2, vcc, s33, v2
	s_nop 1
	v_addc_co_u32_e32 v3, vcc, 0, v3, vcc
	global_load_dwordx4 v[60:63], v[2:3], off
	global_load_dwordx4 v[36:39], v[2:3], off offset:1024
	global_load_dwordx4 v[48:51], v[2:3], off offset:2048
	global_load_dwordx4 v[28:31], v[2:3], off offset:3072
	v_cmp_eq_u32_e32 vcc, s11, v93
	v_add_u32_e32 v96, 64, v96
	v_add_u32_e32 v95, 64, v95
	s_or_b64 s[20:21], vcc, s[20:21]
	v_mov_b32_e32 v97, v99
	s_mov_b32 s11, s22
	s_andn2_b64 exec, exec, s[20:21]
	s_cbranch_execz .LBB0_105
